# write-through (sc1) output stores in the single-tile GEMM phases (branch merge, out-proj residual) so the grid barrier's L2 write-back has less to flush
# baseline (speedup 1.0000x reference)
.LBB0_174:
	s_add_u32 s40, s22, 0x100
	s_addc_u32 s41, s23, 0
	s_add_i32 s83, 0, 0x10000
	v_add_u32_e32 v148, s83, v157
	ds_read_b128 v[130:133], v148
	ds_read_b128 v[134:137], v148 offset:1024
	ds_read_b128 v[138:141], v148 offset:2048
	ds_read_b128 v[148:151], v148 offset:3072
	s_cmp_eq_u32 s82, 12
	s_cselect_b32 s49, s9, s41
	s_cselect_b32 s48, s12, s40
	s_cselect_b32 s43, s5, s79
	s_cselect_b32 s42, s34, s61
	v_lshl_add_u64 v[188:189], s[22:23], 0, v[146:147]
	s_add_i32 m0, s19, 0xc000
	ds_read_b128 v[152:155], v159
	ds_read_b128 v[160:163], v159 offset:1024
	ds_read_b128 v[164:167], v159 offset:2048
	ds_read_b128 v[168:171], v159 offset:3072
	ds_read_b128 v[172:175], v159 offset:4096
	ds_read_b128 v[176:179], v159 offset:5120
	ds_read_b128 v[180:183], v159 offset:6144
	ds_read_b128 v[184:187], v159 offset:7168
	global_load_lds_dwordx4 v[188:189], off
	v_lshl_add_u64 v[188:189], s[22:23], 0, v[144:145]
	s_add_i32 m0, s19, 0xe000
	s_nop 0
	global_load_lds_dwordx4 v[188:189], off
	s_waitcnt lgkmcnt(8)
	s_waitcnt vmcnt(10)
	s_barrier
	s_waitcnt lgkmcnt(0)
	s_waitcnt lgkmcnt(0)
	v_mfma_f32_16x16x32_bf16 v[126:129], v[130:133], v[152:155], v[126:129]
	v_mfma_f32_16x16x32_bf16 v[122:125], v[138:141], v[152:155], v[122:125]
	v_mfma_f32_16x16x32_bf16 v[118:121], v[130:133], v[164:167], v[118:121]
	v_mfma_f32_16x16x32_bf16 v[106:109], v[138:141], v[164:167], v[106:109]
	v_mfma_f32_16x16x32_bf16 v[102:105], v[130:133], v[172:175], v[102:105]
	v_mfma_f32_16x16x32_bf16 v[90:93], v[138:141], v[172:175], v[90:93]
	v_mfma_f32_16x16x32_bf16 v[86:89], v[130:133], v[180:183], v[86:89]
	v_mfma_f32_16x16x32_bf16 v[74:77], v[138:141], v[180:183], v[74:77]
	v_mfma_f32_16x16x32_bf16 v[126:129], v[134:137], v[160:163], v[126:129]
	v_mfma_f32_16x16x32_bf16 v[122:125], v[148:151], v[160:163], v[122:125]
	v_mfma_f32_16x16x32_bf16 v[118:121], v[134:137], v[168:171], v[118:121]
	v_mfma_f32_16x16x32_bf16 v[106:109], v[148:151], v[168:171], v[106:109]
	v_mfma_f32_16x16x32_bf16 v[102:105], v[134:137], v[176:179], v[102:105]
	v_mfma_f32_16x16x32_bf16 v[90:93], v[148:151], v[176:179], v[90:93]
	v_mfma_f32_16x16x32_bf16 v[86:89], v[134:137], v[184:187], v[86:89]
	v_mfma_f32_16x16x32_bf16 v[74:77], v[148:151], v[184:187], v[74:77]
	s_barrier
	s_add_i32 s84, 0, 0x14000
	v_add_u32_e32 v196, s84, v157
	s_add_i32 s22, s83, s52
	ds_read_b128 v[188:191], v196
	ds_read_b128 v[192:195], v196 offset:1024
	ds_read_b128 v[208:211], v196 offset:2048
	ds_read_b128 v[212:215], v196 offset:3072
	v_lshl_add_u64 v[196:197], s[42:43], 0, v[16:17]
	s_mov_b32 m0, s22
	v_lshl_add_u64 v[216:217], s[42:43], 0, v[142:143]
	global_load_lds_dwordx4 v[196:197], off
	s_add_i32 m0, s22, 0x2000
	s_nop 0
	global_load_lds_dwordx4 v[216:217], off
	s_waitcnt vmcnt(10)
	s_barrier
	s_waitcnt lgkmcnt(0)
	s_waitcnt lgkmcnt(0)
	v_mfma_f32_16x16x32_bf16 v[114:117], v[188:191], v[152:155], v[114:117]
	v_mfma_f32_16x16x32_bf16 v[110:113], v[208:211], v[152:155], v[110:113]
	v_mfma_f32_16x16x32_bf16 v[98:101], v[188:191], v[164:167], v[98:101]
	v_mfma_f32_16x16x32_bf16 v[94:97], v[208:211], v[164:167], v[94:97]
	v_mfma_f32_16x16x32_bf16 v[82:85], v[188:191], v[172:175], v[82:85]
	v_mfma_f32_16x16x32_bf16 v[78:81], v[208:211], v[172:175], v[78:81]
	v_mfma_f32_16x16x32_bf16 v[70:73], v[188:191], v[180:183], v[70:73]
	v_mfma_f32_16x16x32_bf16 v[66:69], v[208:211], v[180:183], v[66:69]
	v_mfma_f32_16x16x32_bf16 v[114:117], v[192:195], v[160:163], v[114:117]
	v_mfma_f32_16x16x32_bf16 v[110:113], v[212:215], v[160:163], v[110:113]
	v_mfma_f32_16x16x32_bf16 v[98:101], v[192:195], v[168:171], v[98:101]
	v_mfma_f32_16x16x32_bf16 v[94:97], v[212:215], v[168:171], v[94:97]
	v_mfma_f32_16x16x32_bf16 v[82:85], v[192:195], v[176:179], v[82:85]
	v_mfma_f32_16x16x32_bf16 v[78:81], v[212:215], v[176:179], v[78:81]
	v_mfma_f32_16x16x32_bf16 v[70:73], v[192:195], v[184:187], v[70:73]
	v_mfma_f32_16x16x32_bf16 v[66:69], v[212:215], v[184:187], v[66:69]
	s_mov_b32 m0, s19
	v_lshl_add_u64 v[218:219], s[48:49], 0, v[16:17]
	s_barrier
	ds_read_b128 v[152:155], v159 offset:16384
	ds_read_b128 v[160:163], v159 offset:17408
	ds_read_b128 v[164:167], v159 offset:18432
	ds_read_b128 v[168:171], v159 offset:19456
	ds_read_b128 v[172:175], v159 offset:20480
	ds_read_b128 v[176:179], v159 offset:21504
	ds_read_b128 v[180:183], v159 offset:22528
	ds_read_b128 v[184:187], v159 offset:23552
	global_load_lds_dwordx4 v[218:219], off
	v_lshl_add_u64 v[220:221], s[48:49], 0, v[142:143]
	s_mov_b32 m0, s54
	s_nop 0
	global_load_lds_dwordx4 v[220:221], off
	s_barrier
	s_waitcnt lgkmcnt(0)
	s_waitcnt lgkmcnt(0)
	v_mfma_f32_16x16x32_bf16 v[62:65], v[130:133], v[152:155], v[62:65]
	v_mfma_f32_16x16x32_bf16 v[58:61], v[138:141], v[152:155], v[58:61]
	v_mfma_f32_16x16x32_bf16 v[54:57], v[130:133], v[164:167], v[54:57]
	v_mfma_f32_16x16x32_bf16 v[50:53], v[138:141], v[164:167], v[50:53]
	v_mfma_f32_16x16x32_bf16 v[46:49], v[130:133], v[172:175], v[46:49]
	v_mfma_f32_16x16x32_bf16 v[38:41], v[138:141], v[172:175], v[38:41]
	v_mfma_f32_16x16x32_bf16 v[30:33], v[130:133], v[180:183], v[30:33]
	v_mfma_f32_16x16x32_bf16 v[18:21], v[138:141], v[180:183], v[18:21]
	v_mfma_f32_16x16x32_bf16 v[62:65], v[134:137], v[160:163], v[62:65]
	v_mfma_f32_16x16x32_bf16 v[58:61], v[148:151], v[160:163], v[58:61]
	v_mfma_f32_16x16x32_bf16 v[54:57], v[134:137], v[168:171], v[54:57]
	v_mfma_f32_16x16x32_bf16 v[50:53], v[148:151], v[168:171], v[50:53]
	v_mfma_f32_16x16x32_bf16 v[46:49], v[134:137], v[176:179], v[46:49]
	v_mfma_f32_16x16x32_bf16 v[38:41], v[148:151], v[176:179], v[38:41]
	v_mfma_f32_16x16x32_bf16 v[30:33], v[134:137], v[184:187], v[30:33]
	v_mfma_f32_16x16x32_bf16 v[18:21], v[148:151], v[184:187], v[18:21]
	s_barrier
	s_add_u32 s22, s42, 0x40000
	s_addc_u32 s23, s43, 0
	s_add_i32 s83, s84, s52
	v_lshl_add_u64 v[130:131], s[22:23], 0, v[16:17]
	s_mov_b32 m0, s83
	s_nop 0
	global_load_lds_dwordx4 v[130:131], off
	v_lshl_add_u64 v[130:131], s[22:23], 0, v[142:143]
	s_add_i32 m0, s83, 0x2000
	s_nop 0
	global_load_lds_dwordx4 v[130:131], off
	s_waitcnt vmcnt(10)
	s_barrier
	v_mfma_f32_16x16x32_bf16 v[42:45], v[188:191], v[152:155], v[42:45]
	v_mfma_f32_16x16x32_bf16 v[34:37], v[208:211], v[152:155], v[34:37]
	v_mfma_f32_16x16x32_bf16 v[26:29], v[188:191], v[164:167], v[26:29]
	v_mfma_f32_16x16x32_bf16 v[22:25], v[208:211], v[164:167], v[22:25]
	v_mfma_f32_16x16x32_bf16 v[12:15], v[188:191], v[172:175], v[12:15]
	v_mfma_f32_16x16x32_bf16 v[8:11], v[208:211], v[172:175], v[8:11]
	v_mfma_f32_16x16x32_bf16 v[4:7], v[188:191], v[180:183], v[4:7]
	v_mfma_f32_16x16x32_bf16 v[0:3], v[208:211], v[180:183], v[0:3]
	v_mfma_f32_16x16x32_bf16 v[42:45], v[192:195], v[160:163], v[42:45]
	v_mfma_f32_16x16x32_bf16 v[34:37], v[212:215], v[160:163], v[34:37]
	v_mfma_f32_16x16x32_bf16 v[26:29], v[192:195], v[168:171], v[26:29]
	v_mfma_f32_16x16x32_bf16 v[22:25], v[212:215], v[168:171], v[22:25]
	v_mfma_f32_16x16x32_bf16 v[12:15], v[192:195], v[176:179], v[12:15]
	v_mfma_f32_16x16x32_bf16 v[8:11], v[212:215], v[176:179], v[8:11]
	v_mfma_f32_16x16x32_bf16 v[4:7], v[192:195], v[184:187], v[4:7]
	v_mfma_f32_16x16x32_bf16 v[0:3], v[212:215], v[184:187], v[0:3]
	s_add_i32 s83, 0, 0x18000
	v_add_u32_e32 v148, s83, v157
	s_barrier
	ds_read_b128 v[130:133], v148
	ds_read_b128 v[134:137], v148 offset:1024
	ds_read_b128 v[138:141], v148 offset:2048
	ds_read_b128 v[148:151], v148 offset:3072
	s_add_u32 s22, s48, 0x40000
	s_addc_u32 s23, s49, 0
	s_mov_b32 m0, s55
	v_lshl_add_u64 v[188:189], s[22:23], 0, v[16:17]
	ds_read_b128 v[152:155], v159 offset:32768
	ds_read_b128 v[160:163], v159 offset:33792
	ds_read_b128 v[164:167], v159 offset:34816
	ds_read_b128 v[168:171], v159 offset:35840
	ds_read_b128 v[172:175], v159 offset:36864
	ds_read_b128 v[176:179], v159 offset:37888
	ds_read_b128 v[180:183], v159 offset:38912
	ds_read_b128 v[184:187], v159 offset:39936
	global_load_lds_dwordx4 v[188:189], off
	v_lshl_add_u64 v[188:189], s[22:23], 0, v[142:143]
	s_mov_b32 m0, s56
	s_nop 0
	global_load_lds_dwordx4 v[188:189], off
	s_waitcnt lgkmcnt(8)
	s_waitcnt vmcnt(10)
	s_barrier
	s_waitcnt lgkmcnt(0)
	s_waitcnt lgkmcnt(0)
	v_mfma_f32_16x16x32_bf16 v[126:129], v[130:133], v[152:155], v[126:129]
	v_mfma_f32_16x16x32_bf16 v[122:125], v[138:141], v[152:155], v[122:125]
	v_mfma_f32_16x16x32_bf16 v[118:121], v[130:133], v[164:167], v[118:121]
	v_mfma_f32_16x16x32_bf16 v[106:109], v[138:141], v[164:167], v[106:109]
	v_mfma_f32_16x16x32_bf16 v[102:105], v[130:133], v[172:175], v[102:105]
	v_mfma_f32_16x16x32_bf16 v[90:93], v[138:141], v[172:175], v[90:93]
	v_mfma_f32_16x16x32_bf16 v[86:89], v[130:133], v[180:183], v[86:89]
	v_mfma_f32_16x16x32_bf16 v[74:77], v[138:141], v[180:183], v[74:77]
	v_mfma_f32_16x16x32_bf16 v[126:129], v[134:137], v[160:163], v[126:129]
	v_mfma_f32_16x16x32_bf16 v[122:125], v[148:151], v[160:163], v[122:125]
	v_mfma_f32_16x16x32_bf16 v[118:121], v[134:137], v[168:171], v[118:121]
	v_mfma_f32_16x16x32_bf16 v[106:109], v[148:151], v[168:171], v[106:109]
	v_mfma_f32_16x16x32_bf16 v[102:105], v[134:137], v[176:179], v[102:105]
	v_mfma_f32_16x16x32_bf16 v[90:93], v[148:151], v[176:179], v[90:93]
	v_mfma_f32_16x16x32_bf16 v[86:89], v[134:137], v[184:187], v[86:89]
	v_mfma_f32_16x16x32_bf16 v[74:77], v[148:151], v[184:187], v[74:77]
	s_barrier
	s_add_i32 s48, 0, 0x1c000
	s_add_i32 s22, s83, s52
	v_add_u32_e32 v212, s48, v157
	v_lshl_add_u64 v[196:197], v[196:197], 0, s[10:11]
	s_mov_b32 m0, s22
	ds_read_b128 v[188:191], v212
	ds_read_b128 v[192:195], v212 offset:1024
	ds_read_b128 v[208:211], v212 offset:2048
	ds_read_b128 v[212:215], v212 offset:3072
	global_load_lds_dwordx4 v[196:197], off
	v_lshl_add_u64 v[196:197], v[216:217], 0, s[10:11]
	s_add_i32 m0, s22, 0x2000
	s_nop 0
	global_load_lds_dwordx4 v[196:197], off
	s_waitcnt vmcnt(10)
	s_barrier
	s_waitcnt lgkmcnt(0)
	s_waitcnt lgkmcnt(0)
	v_mfma_f32_16x16x32_bf16 v[114:117], v[188:191], v[152:155], v[114:117]
	v_mfma_f32_16x16x32_bf16 v[110:113], v[208:211], v[152:155], v[110:113]
	v_mfma_f32_16x16x32_bf16 v[98:101], v[188:191], v[164:167], v[98:101]
	v_mfma_f32_16x16x32_bf16 v[94:97], v[208:211], v[164:167], v[94:97]
	v_mfma_f32_16x16x32_bf16 v[82:85], v[188:191], v[172:175], v[82:85]
	v_mfma_f32_16x16x32_bf16 v[78:81], v[208:211], v[172:175], v[78:81]
	v_mfma_f32_16x16x32_bf16 v[70:73], v[188:191], v[180:183], v[70:73]
	v_mfma_f32_16x16x32_bf16 v[66:69], v[208:211], v[180:183], v[66:69]
	v_mfma_f32_16x16x32_bf16 v[114:117], v[192:195], v[160:163], v[114:117]
	v_mfma_f32_16x16x32_bf16 v[110:113], v[212:215], v[160:163], v[110:113]
	v_mfma_f32_16x16x32_bf16 v[98:101], v[192:195], v[168:171], v[98:101]
	v_mfma_f32_16x16x32_bf16 v[94:97], v[212:215], v[168:171], v[94:97]
	v_mfma_f32_16x16x32_bf16 v[82:85], v[192:195], v[176:179], v[82:85]
	v_mfma_f32_16x16x32_bf16 v[78:81], v[212:215], v[176:179], v[78:81]
	v_mfma_f32_16x16x32_bf16 v[70:73], v[192:195], v[184:187], v[70:73]
	v_mfma_f32_16x16x32_bf16 v[66:69], v[212:215], v[184:187], v[66:69]
	s_mov_b32 m0, s57
	v_lshl_add_u64 v[196:197], v[218:219], 0, s[10:11]
	s_barrier
	ds_read_b128 v[152:155], v159 offset:49152
	ds_read_b128 v[160:163], v159 offset:50176
	ds_read_b128 v[164:167], v159 offset:51200
	ds_read_b128 v[168:171], v159 offset:52224
	ds_read_b128 v[172:175], v159 offset:53248
	ds_read_b128 v[176:179], v159 offset:54272
	ds_read_b128 v[180:183], v159 offset:55296
	ds_read_b128 v[184:187], v159 offset:56320
	global_load_lds_dwordx4 v[196:197], off
	v_lshl_add_u64 v[196:197], v[220:221], 0, s[10:11]
	s_mov_b32 m0, s58
	s_nop 0
	global_load_lds_dwordx4 v[196:197], off
	s_barrier
	s_waitcnt lgkmcnt(0)
	s_waitcnt lgkmcnt(0)
	v_mfma_f32_16x16x32_bf16 v[62:65], v[130:133], v[152:155], v[62:65]
	v_mfma_f32_16x16x32_bf16 v[58:61], v[138:141], v[152:155], v[58:61]
	v_mfma_f32_16x16x32_bf16 v[54:57], v[130:133], v[164:167], v[54:57]
	v_mfma_f32_16x16x32_bf16 v[50:53], v[138:141], v[164:167], v[50:53]
	v_mfma_f32_16x16x32_bf16 v[46:49], v[130:133], v[172:175], v[46:49]
	v_mfma_f32_16x16x32_bf16 v[38:41], v[138:141], v[172:175], v[38:41]
	v_mfma_f32_16x16x32_bf16 v[30:33], v[130:133], v[180:183], v[30:33]
	v_mfma_f32_16x16x32_bf16 v[18:21], v[138:141], v[180:183], v[18:21]
	v_mfma_f32_16x16x32_bf16 v[62:65], v[134:137], v[160:163], v[62:65]
	v_mfma_f32_16x16x32_bf16 v[58:61], v[148:151], v[160:163], v[58:61]
	v_mfma_f32_16x16x32_bf16 v[54:57], v[134:137], v[168:171], v[54:57]
	v_mfma_f32_16x16x32_bf16 v[50:53], v[148:151], v[168:171], v[50:53]
	v_mfma_f32_16x16x32_bf16 v[46:49], v[134:137], v[176:179], v[46:49]
	v_mfma_f32_16x16x32_bf16 v[38:41], v[148:151], v[176:179], v[38:41]
	v_mfma_f32_16x16x32_bf16 v[30:33], v[134:137], v[184:187], v[30:33]
	v_mfma_f32_16x16x32_bf16 v[18:21], v[148:151], v[184:187], v[18:21]
	s_barrier
	s_add_u32 s22, s42, 0x40080
	s_addc_u32 s23, s43, 0
	s_add_i32 s42, s48, s52
	v_lshl_add_u64 v[130:131], s[22:23], 0, v[16:17]
	s_mov_b32 m0, s42
	s_nop 0
	global_load_lds_dwordx4 v[130:131], off
	v_lshl_add_u64 v[130:131], s[22:23], 0, v[142:143]
	s_add_i32 m0, s42, 0x2000
	s_nop 0
	global_load_lds_dwordx4 v[130:131], off
	s_waitcnt vmcnt(10)
	s_barrier
	v_mfma_f32_16x16x32_bf16 v[42:45], v[188:191], v[152:155], v[42:45]
	v_mfma_f32_16x16x32_bf16 v[34:37], v[208:211], v[152:155], v[34:37]
	v_mfma_f32_16x16x32_bf16 v[26:29], v[188:191], v[164:167], v[26:29]
	v_mfma_f32_16x16x32_bf16 v[22:25], v[208:211], v[164:167], v[22:25]
	v_mfma_f32_16x16x32_bf16 v[12:15], v[188:191], v[172:175], v[12:15]
	v_mfma_f32_16x16x32_bf16 v[8:11], v[208:211], v[172:175], v[8:11]
	v_mfma_f32_16x16x32_bf16 v[4:7], v[188:191], v[180:183], v[4:7]
	v_mfma_f32_16x16x32_bf16 v[0:3], v[208:211], v[180:183], v[0:3]
	v_mfma_f32_16x16x32_bf16 v[42:45], v[192:195], v[160:163], v[42:45]
	v_mfma_f32_16x16x32_bf16 v[34:37], v[212:215], v[160:163], v[34:37]
	v_mfma_f32_16x16x32_bf16 v[26:29], v[192:195], v[168:171], v[26:29]
	v_mfma_f32_16x16x32_bf16 v[22:25], v[212:215], v[168:171], v[22:25]
	v_mfma_f32_16x16x32_bf16 v[12:15], v[192:195], v[176:179], v[12:15]
	v_mfma_f32_16x16x32_bf16 v[8:11], v[212:215], v[176:179], v[8:11]
	v_mfma_f32_16x16x32_bf16 v[4:7], v[192:195], v[184:187], v[4:7]
	v_mfma_f32_16x16x32_bf16 v[0:3], v[212:215], v[184:187], v[0:3]
	s_add_i32 s82, s82, 2
	s_add_u32 s61, s61, 0x100
	s_addc_u32 s79, s79, 0
	s_cmp_gt_u32 s82, 13
	s_mov_b64 s[22:23], s[40:41]
	s_barrier
	s_cbranch_scc0 .LBB0_174
	v_lshl_or_b32 v242, s2, 8, v158
	v_lshl_add_u32 v243, s18, 8, v156
	v_lshlrev_b32_e32 v242, 2, v242
	v_lshl_add_u32 v242, v243, 12, v242
	v_and_b32_e32 v243, 8, v156
	v_mul_u32_u24_e32 v244, 0xff8, v243
	v_sub_u32_e32 v148, v242, v244
	v_sub_u32_e32 v243, 8, v243
	v_mul_u32_u24_e32 v244, 0x1008, v243
	v_add_u32_e32 v196, v242, v244
	v_add_u32_e32 v149, 0x10000, v148
	v_add_u32_e32 v197, 0x10000, v196
	v_add_u32_e32 v150, 0x20000, v148
	v_add_u32_e32 v224, 0x20000, v196
	v_add_u32_e32 v151, 0x30000, v148
	v_add_u32_e32 v225, 0x30000, v196
	v_add_u32_e32 v152, 0x80000, v148
	v_add_u32_e32 v226, 0x80000, v196
	v_add_u32_e32 v153, 0x90000, v148
	v_add_u32_e32 v227, 0x90000, v196
	v_add_u32_e32 v154, 0xa0000, v148
	v_add_u32_e32 v240, 0xa0000, v196
	v_add_u32_e32 v155, 0xb0000, v148
	v_add_u32_e32 v241, 0xb0000, v196
	global_load_dwordx4 v[160:163], v148, s[20:21]
	global_load_dwordx4 v[164:167], v196, s[20:21]
	global_load_dwordx4 v[168:171], v148, s[20:21] offset:512
	global_load_dwordx4 v[172:175], v196, s[20:21] offset:512
	global_load_dwordx4 v[176:179], v149, s[20:21]
	global_load_dwordx4 v[180:183], v197, s[20:21]
	global_load_dwordx4 v[184:187], v149, s[20:21] offset:512
	global_load_dwordx4 v[188:191], v197, s[20:21] offset:512
	global_load_dwordx4 v[192:195], v150, s[20:21]
	global_load_dwordx4 v[208:211], v224, s[20:21]
	global_load_dwordx4 v[212:215], v150, s[20:21] offset:512
	global_load_dwordx4 v[216:219], v224, s[20:21] offset:512
	global_load_dwordx4 v[220:223], v151, s[20:21]
	global_load_dwordx4 v[138:141], v225, s[20:21]
	global_load_dwordx4 v[134:137], v151, s[20:21] offset:512
	global_load_dwordx4 v[130:133], v225, s[20:21] offset:512
	v_mov_b32_dpp v122, v122 row_ror:8 row_mask:0xf bank_mask:0xf
	v_mov_b32_dpp v123, v123 row_ror:8 row_mask:0xf bank_mask:0xf
	v_mov_b32_dpp v124, v124 row_ror:8 row_mask:0xf bank_mask:0xf
	v_mov_b32_dpp v125, v125 row_ror:8 row_mask:0xf bank_mask:0xf
	v_mov_b32_dpp v110, v110 row_ror:8 row_mask:0xf bank_mask:0xf
	v_mov_b32_dpp v111, v111 row_ror:8 row_mask:0xf bank_mask:0xf
	v_mov_b32_dpp v112, v112 row_ror:8 row_mask:0xf bank_mask:0xf
	v_mov_b32_dpp v113, v113 row_ror:8 row_mask:0xf bank_mask:0xf
	v_mov_b32_dpp v106, v106 row_ror:8 row_mask:0xf bank_mask:0xf
	v_mov_b32_dpp v107, v107 row_ror:8 row_mask:0xf bank_mask:0xf
	v_mov_b32_dpp v108, v108 row_ror:8 row_mask:0xf bank_mask:0xf
	v_mov_b32_dpp v109, v109 row_ror:8 row_mask:0xf bank_mask:0xf
	v_mov_b32_dpp v94, v94 row_ror:8 row_mask:0xf bank_mask:0xf
	v_mov_b32_dpp v95, v95 row_ror:8 row_mask:0xf bank_mask:0xf
	v_mov_b32_dpp v96, v96 row_ror:8 row_mask:0xf bank_mask:0xf
	v_mov_b32_dpp v97, v97 row_ror:8 row_mask:0xf bank_mask:0xf
	v_mov_b32_dpp v90, v90 row_ror:8 row_mask:0xf bank_mask:0xf
	v_mov_b32_dpp v91, v91 row_ror:8 row_mask:0xf bank_mask:0xf
	v_mov_b32_dpp v92, v92 row_ror:8 row_mask:0xf bank_mask:0xf
	v_mov_b32_dpp v93, v93 row_ror:8 row_mask:0xf bank_mask:0xf
	v_mov_b32_dpp v78, v78 row_ror:8 row_mask:0xf bank_mask:0xf
	v_mov_b32_dpp v79, v79 row_ror:8 row_mask:0xf bank_mask:0xf
	v_mov_b32_dpp v80, v80 row_ror:8 row_mask:0xf bank_mask:0xf
	v_mov_b32_dpp v81, v81 row_ror:8 row_mask:0xf bank_mask:0xf
	v_mov_b32_dpp v74, v74 row_ror:8 row_mask:0xf bank_mask:0xf
	v_mov_b32_dpp v75, v75 row_ror:8 row_mask:0xf bank_mask:0xf
	v_mov_b32_dpp v76, v76 row_ror:8 row_mask:0xf bank_mask:0xf
	v_mov_b32_dpp v77, v77 row_ror:8 row_mask:0xf bank_mask:0xf
	v_mov_b32_dpp v66, v66 row_ror:8 row_mask:0xf bank_mask:0xf
	v_mov_b32_dpp v67, v67 row_ror:8 row_mask:0xf bank_mask:0xf
	v_mov_b32_dpp v68, v68 row_ror:8 row_mask:0xf bank_mask:0xf
	v_mov_b32_dpp v69, v69 row_ror:8 row_mask:0xf bank_mask:0xf
	s_mov_b32 exec_lo, 0xff00ff00
	s_mov_b32 exec_hi, 0xff00ff00
	v_swap_b32 v126, v122
	v_swap_b32 v127, v123
	v_swap_b32 v128, v124
	v_swap_b32 v129, v125
	v_swap_b32 v114, v110
	v_swap_b32 v115, v111
	v_swap_b32 v116, v112
	v_swap_b32 v117, v113
	v_swap_b32 v118, v106
	v_swap_b32 v119, v107
	v_swap_b32 v120, v108
	v_swap_b32 v121, v109
	v_swap_b32 v98, v94
	v_swap_b32 v99, v95
	v_swap_b32 v100, v96
	v_swap_b32 v101, v97
	v_swap_b32 v102, v90
	v_swap_b32 v103, v91
	v_swap_b32 v104, v92
	v_swap_b32 v105, v93
	v_swap_b32 v82, v78
	v_swap_b32 v83, v79
	v_swap_b32 v84, v80
	v_swap_b32 v85, v81
	v_swap_b32 v86, v74
	v_swap_b32 v87, v75
	v_swap_b32 v88, v76
	v_swap_b32 v89, v77
	v_swap_b32 v70, v66
	v_swap_b32 v71, v67
	v_swap_b32 v72, v68
	v_swap_b32 v73, v69
	s_mov_b64 exec, -1
	s_waitcnt vmcnt(12)
	v_pk_add_f32 v[126:127], v[126:127], v[160:161]
	v_pk_add_f32 v[128:129], v[128:129], v[162:163]
	v_pk_add_f32 v[122:123], v[122:123], v[164:165]
	v_pk_add_f32 v[124:125], v[124:125], v[166:167]
	v_pk_add_f32 v[114:115], v[114:115], v[168:169]
	v_pk_add_f32 v[116:117], v[116:117], v[170:171]
	v_pk_add_f32 v[110:111], v[110:111], v[172:173]
	v_pk_add_f32 v[112:113], v[112:113], v[174:175]
	s_waitcnt vmcnt(8)
	v_pk_add_f32 v[118:119], v[118:119], v[176:177]
	v_pk_add_f32 v[120:121], v[120:121], v[178:179]
	v_pk_add_f32 v[106:107], v[106:107], v[180:181]
	v_pk_add_f32 v[108:109], v[108:109], v[182:183]
	v_pk_add_f32 v[98:99], v[98:99], v[184:185]
	v_pk_add_f32 v[100:101], v[100:101], v[186:187]
	v_pk_add_f32 v[94:95], v[94:95], v[188:189]
	v_pk_add_f32 v[96:97], v[96:97], v[190:191]
	s_waitcnt vmcnt(4)
	v_pk_add_f32 v[102:103], v[102:103], v[192:193]
	v_pk_add_f32 v[104:105], v[104:105], v[194:195]
	v_pk_add_f32 v[90:91], v[90:91], v[208:209]
	v_pk_add_f32 v[92:93], v[92:93], v[210:211]
	v_pk_add_f32 v[82:83], v[82:83], v[212:213]
	v_pk_add_f32 v[84:85], v[84:85], v[214:215]
	v_pk_add_f32 v[78:79], v[78:79], v[216:217]
	v_pk_add_f32 v[80:81], v[80:81], v[218:219]
	s_waitcnt vmcnt(0)
	v_pk_add_f32 v[86:87], v[86:87], v[220:221]
	v_pk_add_f32 v[88:89], v[88:89], v[222:223]
	v_pk_add_f32 v[74:75], v[74:75], v[138:139]
	v_pk_add_f32 v[76:77], v[76:77], v[140:141]
	v_pk_add_f32 v[70:71], v[70:71], v[134:135]
	v_pk_add_f32 v[72:73], v[72:73], v[136:137]
	v_pk_add_f32 v[66:67], v[66:67], v[130:131]
	v_pk_add_f32 v[68:69], v[68:69], v[132:133]
	global_load_dwordx4 v[160:163], v152, s[20:21]
	global_load_dwordx4 v[164:167], v226, s[20:21]
	global_load_dwordx4 v[168:171], v152, s[20:21] offset:512
	global_load_dwordx4 v[172:175], v226, s[20:21] offset:512
	global_load_dwordx4 v[176:179], v153, s[20:21]
	global_load_dwordx4 v[180:183], v227, s[20:21]
	global_load_dwordx4 v[184:187], v153, s[20:21] offset:512
	global_load_dwordx4 v[188:191], v227, s[20:21] offset:512
	global_load_dwordx4 v[192:195], v154, s[20:21]
	global_load_dwordx4 v[208:211], v240, s[20:21]
	global_load_dwordx4 v[212:215], v154, s[20:21] offset:512
	global_load_dwordx4 v[216:219], v240, s[20:21] offset:512
	global_load_dwordx4 v[220:223], v155, s[20:21]
	global_load_dwordx4 v[138:141], v241, s[20:21]
	global_load_dwordx4 v[134:137], v155, s[20:21] offset:512
	global_load_dwordx4 v[130:133], v241, s[20:21] offset:512
	s_nop 4
	v_mov_b32_dpp v58, v58 row_ror:8 row_mask:0xf bank_mask:0xf
	v_mov_b32_dpp v59, v59 row_ror:8 row_mask:0xf bank_mask:0xf
	v_mov_b32_dpp v60, v60 row_ror:8 row_mask:0xf bank_mask:0xf
	v_mov_b32_dpp v61, v61 row_ror:8 row_mask:0xf bank_mask:0xf
	v_mov_b32_dpp v34, v34 row_ror:8 row_mask:0xf bank_mask:0xf
	v_mov_b32_dpp v35, v35 row_ror:8 row_mask:0xf bank_mask:0xf
	v_mov_b32_dpp v36, v36 row_ror:8 row_mask:0xf bank_mask:0xf
	v_mov_b32_dpp v37, v37 row_ror:8 row_mask:0xf bank_mask:0xf
	v_mov_b32_dpp v50, v50 row_ror:8 row_mask:0xf bank_mask:0xf
	v_mov_b32_dpp v51, v51 row_ror:8 row_mask:0xf bank_mask:0xf
	v_mov_b32_dpp v52, v52 row_ror:8 row_mask:0xf bank_mask:0xf
	v_mov_b32_dpp v53, v53 row_ror:8 row_mask:0xf bank_mask:0xf
	v_mov_b32_dpp v22, v22 row_ror:8 row_mask:0xf bank_mask:0xf
	v_mov_b32_dpp v23, v23 row_ror:8 row_mask:0xf bank_mask:0xf
	v_mov_b32_dpp v24, v24 row_ror:8 row_mask:0xf bank_mask:0xf
	v_mov_b32_dpp v25, v25 row_ror:8 row_mask:0xf bank_mask:0xf
	v_mov_b32_dpp v38, v38 row_ror:8 row_mask:0xf bank_mask:0xf
	v_mov_b32_dpp v39, v39 row_ror:8 row_mask:0xf bank_mask:0xf
	v_mov_b32_dpp v40, v40 row_ror:8 row_mask:0xf bank_mask:0xf
	v_mov_b32_dpp v41, v41 row_ror:8 row_mask:0xf bank_mask:0xf
	v_mov_b32_dpp v8, v8 row_ror:8 row_mask:0xf bank_mask:0xf
	v_mov_b32_dpp v9, v9 row_ror:8 row_mask:0xf bank_mask:0xf
	v_mov_b32_dpp v10, v10 row_ror:8 row_mask:0xf bank_mask:0xf
	v_mov_b32_dpp v11, v11 row_ror:8 row_mask:0xf bank_mask:0xf
	v_mov_b32_dpp v18, v18 row_ror:8 row_mask:0xf bank_mask:0xf
	v_mov_b32_dpp v19, v19 row_ror:8 row_mask:0xf bank_mask:0xf
	v_mov_b32_dpp v20, v20 row_ror:8 row_mask:0xf bank_mask:0xf
	v_mov_b32_dpp v21, v21 row_ror:8 row_mask:0xf bank_mask:0xf
	v_mov_b32_dpp v0, v0 row_ror:8 row_mask:0xf bank_mask:0xf
	v_mov_b32_dpp v1, v1 row_ror:8 row_mask:0xf bank_mask:0xf
	v_mov_b32_dpp v2, v2 row_ror:8 row_mask:0xf bank_mask:0xf
	v_mov_b32_dpp v3, v3 row_ror:8 row_mask:0xf bank_mask:0xf
	s_mov_b32 exec_lo, 0xff00ff00
	s_mov_b32 exec_hi, 0xff00ff00
	v_swap_b32 v62, v58
	v_swap_b32 v63, v59
	v_swap_b32 v64, v60
	v_swap_b32 v65, v61
	v_swap_b32 v42, v34
	v_swap_b32 v43, v35
	v_swap_b32 v44, v36
	v_swap_b32 v45, v37
	v_swap_b32 v54, v50
	v_swap_b32 v55, v51
	v_swap_b32 v56, v52
	v_swap_b32 v57, v53
	v_swap_b32 v26, v22
	v_swap_b32 v27, v23
	v_swap_b32 v28, v24
	v_swap_b32 v29, v25
	v_swap_b32 v46, v38
	v_swap_b32 v47, v39
	v_swap_b32 v48, v40
	v_swap_b32 v49, v41
	v_swap_b32 v12, v8
	v_swap_b32 v13, v9
	v_swap_b32 v14, v10
	v_swap_b32 v15, v11
	v_swap_b32 v30, v18
	v_swap_b32 v31, v19
	v_swap_b32 v32, v20
	v_swap_b32 v33, v21
	v_swap_b32 v4, v0
	v_swap_b32 v5, v1
	v_swap_b32 v6, v2
	v_swap_b32 v7, v3
	s_mov_b64 exec, -1
	global_store_dwordx4 v148, v[126:129], s[20:21] sc1
	global_store_dwordx4 v196, v[122:125], s[20:21] sc1
	global_store_dwordx4 v148, v[114:117], s[20:21] offset:512 sc1
	global_store_dwordx4 v196, v[110:113], s[20:21] offset:512 sc1
	global_store_dwordx4 v149, v[118:121], s[20:21] sc1
	global_store_dwordx4 v197, v[106:109], s[20:21] sc1
	global_store_dwordx4 v149, v[98:101], s[20:21] offset:512 sc1
	global_store_dwordx4 v197, v[94:97], s[20:21] offset:512 sc1
	global_store_dwordx4 v150, v[102:105], s[20:21] sc1
	global_store_dwordx4 v224, v[90:93], s[20:21] sc1
	global_store_dwordx4 v150, v[82:85], s[20:21] offset:512 sc1
	global_store_dwordx4 v224, v[78:81], s[20:21] offset:512 sc1
	global_store_dwordx4 v151, v[86:89], s[20:21] sc1
	global_store_dwordx4 v225, v[74:77], s[20:21] sc1
	global_store_dwordx4 v151, v[70:73], s[20:21] offset:512 sc1
	global_store_dwordx4 v225, v[66:69], s[20:21] offset:512 sc1
	s_waitcnt vmcnt(0)
	v_pk_add_f32 v[62:63], v[62:63], v[160:161]
	v_pk_add_f32 v[64:65], v[64:65], v[162:163]
	v_pk_add_f32 v[58:59], v[58:59], v[164:165]
	v_pk_add_f32 v[60:61], v[60:61], v[166:167]
	v_pk_add_f32 v[42:43], v[42:43], v[168:169]
	v_pk_add_f32 v[44:45], v[44:45], v[170:171]
	v_pk_add_f32 v[34:35], v[34:35], v[172:173]
	v_pk_add_f32 v[36:37], v[36:37], v[174:175]
	v_pk_add_f32 v[54:55], v[54:55], v[176:177]
	v_pk_add_f32 v[56:57], v[56:57], v[178:179]
	v_pk_add_f32 v[50:51], v[50:51], v[180:181]
	v_pk_add_f32 v[52:53], v[52:53], v[182:183]
	v_pk_add_f32 v[26:27], v[26:27], v[184:185]
	v_pk_add_f32 v[28:29], v[28:29], v[186:187]
	v_pk_add_f32 v[22:23], v[22:23], v[188:189]
	v_pk_add_f32 v[24:25], v[24:25], v[190:191]
	v_pk_add_f32 v[46:47], v[46:47], v[192:193]
	v_pk_add_f32 v[48:49], v[48:49], v[194:195]
	v_pk_add_f32 v[38:39], v[38:39], v[208:209]
	v_pk_add_f32 v[40:41], v[40:41], v[210:211]
	v_pk_add_f32 v[12:13], v[12:13], v[212:213]
	v_pk_add_f32 v[14:15], v[14:15], v[214:215]
	v_pk_add_f32 v[8:9], v[8:9], v[216:217]
	v_pk_add_f32 v[10:11], v[10:11], v[218:219]
	v_pk_add_f32 v[30:31], v[30:31], v[220:221]
	v_pk_add_f32 v[32:33], v[32:33], v[222:223]
	v_pk_add_f32 v[18:19], v[18:19], v[138:139]
	v_pk_add_f32 v[20:21], v[20:21], v[140:141]
	v_pk_add_f32 v[4:5], v[4:5], v[134:135]
	v_pk_add_f32 v[6:7], v[6:7], v[136:137]
	v_pk_add_f32 v[0:1], v[0:1], v[130:131]
	v_pk_add_f32 v[2:3], v[2:3], v[132:133]
	global_store_dwordx4 v152, v[62:65], s[20:21] sc1
	global_store_dwordx4 v226, v[58:61], s[20:21] sc1
	global_store_dwordx4 v152, v[42:45], s[20:21] offset:512 sc1
	global_store_dwordx4 v226, v[34:37], s[20:21] offset:512 sc1
	global_store_dwordx4 v153, v[54:57], s[20:21] sc1
	global_store_dwordx4 v227, v[50:53], s[20:21] sc1
	global_store_dwordx4 v153, v[26:29], s[20:21] offset:512 sc1
	global_store_dwordx4 v227, v[22:25], s[20:21] offset:512 sc1
	global_store_dwordx4 v154, v[46:49], s[20:21] sc1
	global_store_dwordx4 v240, v[38:41], s[20:21] sc1
	global_store_dwordx4 v154, v[12:15], s[20:21] offset:512 sc1
	global_store_dwordx4 v240, v[8:11], s[20:21] offset:512 sc1
	global_store_dwordx4 v155, v[30:33], s[20:21] sc1
	global_store_dwordx4 v241, v[18:21], s[20:21] sc1
	global_store_dwordx4 v155, v[4:7], s[20:21] offset:512 sc1
	global_store_dwordx4 v241, v[0:3], s[20:21] offset:512 sc1
	v_readlane_b32 s82, v255, 5
	s_and_b64 vcc, exec, s[38:39]
	s_mov_b32 s2, s4
	s_mov_b32 s18, s8
	s_mov_b64 s[40:41], s[16:17]
	s_mov_b64 s[22:23], s[14:15]
	v_readlane_b32 s83, v255, 6
	s_cbranch_vccz .LBB0_167
	s_waitcnt vmcnt(0)
	s_cmpk_gt_u32 s35, 0xff
	s_cbranch_scc1 .LBB0_178
	s_barrier

.LBB0_234:
	v_lshlrev_b64 v[194:195], 11, v[220:221]
	v_pk_mul_f32 v[142:143], v[142:143], v[0:1]
	v_lshl_add_u64 v[0:1], s[96:97], 0, v[194:195]
	v_pk_mul_f32 v[144:145], v[144:145], v[2:3]
	v_pk_mul_f32 v[138:139], v[138:139], v[4:5]
	v_pk_mul_f32 v[140:141], v[140:141], v[6:7]
	s_andn2_b64 vcc, exec, s[18:19]
	v_lshl_add_u64 v[0:1], v[218:219], 1, v[0:1]
	s_cbranch_vccnz .LBB0_236
	v_cvt_pk_bf16_f32 v2, v142, v143
	v_cvt_pk_bf16_f32 v3, v144, v145
	v_cvt_pk_bf16_f32 v4, v138, v139
	v_cvt_pk_bf16_f32 v5, v140, v141
	global_store_dwordx4 v[0:1], v[2:5], off sc1
	s_nop 1
	v_mul_f32_e32 v2, 0xbfb8aa3b, v248
	v_exp_f32_e32 v2, v2
	s_nop 0
	v_add_f32_e32 v2, 1.0, v2
	v_rcp_f32_e32 v8, v2
	v_mul_f32_e32 v2, 0xbfb8aa3b, v247
	v_exp_f32_e32 v2, v2
	s_nop 0
	v_add_f32_e32 v2, 1.0, v2
	v_rcp_f32_e32 v9, v2
	v_mul_f32_e32 v2, 0xbfb8aa3b, v246
	v_exp_f32_e32 v2, v2
	s_nop 0
	v_add_f32_e32 v2, 1.0, v2
	v_rcp_f32_e32 v10, v2
	v_mul_f32_e32 v2, 0xbfb8aa3b, v245
	v_exp_f32_e32 v2, v2
	s_nop 0
	v_add_f32_e32 v2, 1.0, v2
	v_rcp_f32_e32 v11, v2
	v_mul_f32_e32 v2, 0xbfb8aa3b, v244
	v_exp_f32_e32 v2, v2
	s_nop 0
	v_add_f32_e32 v2, 1.0, v2
	v_rcp_f32_e32 v12, v2
	v_mul_f32_e32 v2, 0xbfb8aa3b, v227
	v_exp_f32_e32 v2, v2
	s_nop 0
	v_add_f32_e32 v2, 1.0, v2
	v_rcp_f32_e32 v13, v2
	v_mul_f32_e32 v2, 0xbfb8aa3b, v225
	v_exp_f32_e32 v2, v2
	s_nop 0
	v_add_f32_e32 v2, 1.0, v2
	v_rcp_f32_e32 v14, v2
	v_mul_f32_e32 v2, 0xbfb8aa3b, v223
	v_exp_f32_e32 v2, v2
	s_nop 0
	v_add_f32_e32 v2, 1.0, v2
	v_rcp_f32_e32 v15, v2
.LBB0_236:
	v_cndmask_b32_e64 v2, 0, 1, s[16:17]
	v_pk_mul_f32 v[110:111], v[110:111], v[8:9]
	v_pk_mul_f32 v[112:113], v[112:113], v[10:11]
	v_pk_mul_f32 v[106:107], v[106:107], v[12:13]
	v_cmp_ne_u32_e64 s[42:43], 1, v2
	s_andn2_b64 vcc, exec, s[16:17]
	v_pk_mul_f32 v[108:109], v[108:109], v[14:15]
	s_cbranch_vccnz .LBB0_238
	v_cvt_pk_bf16_f32 v2, v110, v111
	v_cvt_pk_bf16_f32 v3, v112, v113
	v_cvt_pk_bf16_f32 v4, v106, v107
	v_cvt_pk_bf16_f32 v5, v108, v109
	global_store_dwordx4 v[0:1], v[2:5], off offset:256 sc1

.LBB0_244:
	v_ashrrev_i32_e32 v227, 31, v226
	v_lshlrev_b64 v[178:179], 11, v[226:227]
	v_pk_mul_f32 v[134:135], v[134:135], v[0:1]
	v_lshl_add_u64 v[0:1], s[96:97], 0, v[178:179]
	v_pk_mul_f32 v[136:137], v[136:137], v[2:3]
	v_pk_mul_f32 v[130:131], v[130:131], v[4:5]
	v_pk_mul_f32 v[132:133], v[132:133], v[6:7]
	s_andn2_b64 vcc, exec, s[16:17]
	v_lshl_add_u64 v[0:1], v[218:219], 1, v[0:1]
	s_cbranch_vccnz .LBB0_246
	v_cvt_pk_bf16_f32 v2, v134, v135
	v_cvt_pk_bf16_f32 v3, v136, v137
	v_cvt_pk_bf16_f32 v4, v130, v131
	v_cvt_pk_bf16_f32 v5, v132, v133
	global_store_dwordx4 v[0:1], v[2:5], off sc1
	s_nop 1
	v_mul_f32_e32 v2, 0xbfb8aa3b, v190
	v_exp_f32_e32 v2, v2
	s_nop 0
	v_add_f32_e32 v2, 1.0, v2
	v_rcp_f32_e32 v8, v2
	v_mul_f32_e32 v2, 0xbfb8aa3b, v189
	v_exp_f32_e32 v2, v2
	s_nop 0
	v_add_f32_e32 v2, 1.0, v2
	v_rcp_f32_e32 v9, v2
	v_mul_f32_e32 v2, 0xbfb8aa3b, v188
	v_exp_f32_e32 v2, v2
	s_nop 0
	v_add_f32_e32 v2, 1.0, v2
	v_rcp_f32_e32 v10, v2
	v_mul_f32_e32 v2, 0xbfb8aa3b, v187
	v_exp_f32_e32 v2, v2
	s_nop 0
	v_add_f32_e32 v2, 1.0, v2
	v_rcp_f32_e32 v11, v2
	v_mul_f32_e32 v2, 0xbfb8aa3b, v186
	v_exp_f32_e32 v2, v2
	s_nop 0
	v_add_f32_e32 v2, 1.0, v2
	v_rcp_f32_e32 v12, v2
	v_mul_f32_e32 v2, 0xbfb8aa3b, v184
	v_exp_f32_e32 v2, v2
	s_nop 0
	v_add_f32_e32 v2, 1.0, v2
	v_rcp_f32_e32 v13, v2
	v_mul_f32_e32 v2, 0xbfb8aa3b, v183
	v_exp_f32_e32 v2, v2
	s_nop 0
	v_add_f32_e32 v2, 1.0, v2
	v_rcp_f32_e32 v14, v2
	v_mul_f32_e32 v2, 0xbfb8aa3b, v182
	v_exp_f32_e32 v2, v2
	s_nop 0
	v_add_f32_e32 v2, 1.0, v2
	v_rcp_f32_e32 v15, v2
.LBB0_246:
	v_pk_mul_f32 v[102:103], v[102:103], v[8:9]
	v_pk_mul_f32 v[104:105], v[104:105], v[10:11]
	v_pk_mul_f32 v[98:99], v[98:99], v[12:13]
	s_and_b64 vcc, exec, s[42:43]
	v_pk_mul_f32 v[100:101], v[100:101], v[14:15]
	s_cbranch_vccnz .LBB0_248
	v_cvt_pk_bf16_f32 v2, v102, v103
	v_cvt_pk_bf16_f32 v3, v104, v105
	v_cvt_pk_bf16_f32 v4, v98, v99
	v_cvt_pk_bf16_f32 v5, v100, v101
	global_store_dwordx4 v[0:1], v[2:5], off offset:256 sc1

.LBB0_254:
	v_ashrrev_i32_e32 v225, 31, v224
	v_lshlrev_b64 v[162:163], 11, v[224:225]
	v_pk_mul_f32 v[126:127], v[126:127], v[0:1]
	v_lshl_add_u64 v[0:1], s[96:97], 0, v[162:163]
	v_pk_mul_f32 v[128:129], v[128:129], v[2:3]
	v_pk_mul_f32 v[122:123], v[122:123], v[4:5]
	v_pk_mul_f32 v[124:125], v[124:125], v[6:7]
	s_andn2_b64 vcc, exec, s[16:17]
	v_lshl_add_u64 v[0:1], v[218:219], 1, v[0:1]
	s_cbranch_vccnz .LBB0_256
	v_cvt_pk_bf16_f32 v2, v126, v127
	v_cvt_pk_bf16_f32 v3, v128, v129
	v_cvt_pk_bf16_f32 v4, v122, v123
	v_cvt_pk_bf16_f32 v5, v124, v125
	global_store_dwordx4 v[0:1], v[2:5], off sc1
	s_nop 1
	v_mul_f32_e32 v2, 0xbfb8aa3b, v174
	v_exp_f32_e32 v2, v2
	s_nop 0
	v_add_f32_e32 v2, 1.0, v2
	v_rcp_f32_e32 v8, v2
	v_mul_f32_e32 v2, 0xbfb8aa3b, v173
	v_exp_f32_e32 v2, v2
	s_nop 0
	v_add_f32_e32 v2, 1.0, v2
	v_rcp_f32_e32 v9, v2
	v_mul_f32_e32 v2, 0xbfb8aa3b, v172
	v_exp_f32_e32 v2, v2
	s_nop 0
	v_add_f32_e32 v2, 1.0, v2
	v_rcp_f32_e32 v10, v2
	v_mul_f32_e32 v2, 0xbfb8aa3b, v171
	v_exp_f32_e32 v2, v2
	s_nop 0
	v_add_f32_e32 v2, 1.0, v2
	v_rcp_f32_e32 v11, v2
	v_mul_f32_e32 v2, 0xbfb8aa3b, v170
	v_exp_f32_e32 v2, v2
	s_nop 0
	v_add_f32_e32 v2, 1.0, v2
	v_rcp_f32_e32 v12, v2
	v_mul_f32_e32 v2, 0xbfb8aa3b, v168
	v_exp_f32_e32 v2, v2
	s_nop 0
	v_add_f32_e32 v2, 1.0, v2
	v_rcp_f32_e32 v13, v2
	v_mul_f32_e32 v2, 0xbfb8aa3b, v167
	v_exp_f32_e32 v2, v2
	s_nop 0
	v_add_f32_e32 v2, 1.0, v2
	v_rcp_f32_e32 v14, v2
	v_mul_f32_e32 v2, 0xbfb8aa3b, v166
	v_exp_f32_e32 v2, v2
	s_nop 0
	v_add_f32_e32 v2, 1.0, v2
	v_rcp_f32_e32 v15, v2
.LBB0_256:
	v_pk_mul_f32 v[94:95], v[94:95], v[8:9]
	v_pk_mul_f32 v[96:97], v[96:97], v[10:11]
	v_pk_mul_f32 v[90:91], v[90:91], v[12:13]
	s_and_b64 vcc, exec, s[42:43]
	v_pk_mul_f32 v[92:93], v[92:93], v[14:15]
	s_cbranch_vccnz .LBB0_258
	v_cvt_pk_bf16_f32 v2, v94, v95
	v_cvt_pk_bf16_f32 v3, v96, v97
	v_cvt_pk_bf16_f32 v4, v90, v91
	v_cvt_pk_bf16_f32 v5, v92, v93
	global_store_dwordx4 v[0:1], v[2:5], off offset:256 sc1

.LBB0_264:
	v_ashrrev_i32_e32 v223, 31, v222
	s_waitcnt vmcnt(0) lgkmcnt(0)
	v_lshlrev_b64 v[146:147], 11, v[222:223]
	v_pk_mul_f32 v[118:119], v[118:119], v[0:1]
	v_lshl_add_u64 v[0:1], s[96:97], 0, v[146:147]
	v_pk_mul_f32 v[120:121], v[120:121], v[2:3]
	v_pk_mul_f32 v[114:115], v[114:115], v[4:5]
	v_pk_mul_f32 v[116:117], v[116:117], v[6:7]
	s_andn2_b64 vcc, exec, s[16:17]
	v_lshl_add_u64 v[0:1], v[218:219], 1, v[0:1]
	s_cbranch_vccnz .LBB0_266
	v_cvt_pk_bf16_f32 v2, v118, v119
	v_cvt_pk_bf16_f32 v3, v120, v121
	v_cvt_pk_bf16_f32 v4, v114, v115
	v_cvt_pk_bf16_f32 v5, v116, v117
	global_store_dwordx4 v[0:1], v[2:5], off sc1
	s_nop 1
	v_mul_f32_e32 v2, 0xbfb8aa3b, v158
	v_exp_f32_e32 v2, v2
	s_nop 0
	v_add_f32_e32 v2, 1.0, v2
	v_rcp_f32_e32 v8, v2
	v_mul_f32_e32 v2, 0xbfb8aa3b, v157
	v_exp_f32_e32 v2, v2
	s_nop 0
	v_add_f32_e32 v2, 1.0, v2
	v_rcp_f32_e32 v9, v2
	v_mul_f32_e32 v2, 0xbfb8aa3b, v156
	v_exp_f32_e32 v2, v2
	s_nop 0
	v_add_f32_e32 v2, 1.0, v2
	v_rcp_f32_e32 v10, v2
	v_mul_f32_e32 v2, 0xbfb8aa3b, v155
	v_exp_f32_e32 v2, v2
	s_nop 0
	v_add_f32_e32 v2, 1.0, v2
	v_rcp_f32_e32 v11, v2
	v_mul_f32_e32 v2, 0xbfb8aa3b, v154
	v_exp_f32_e32 v2, v2
	s_nop 0
	v_add_f32_e32 v2, 1.0, v2
	v_rcp_f32_e32 v12, v2
	v_mul_f32_e32 v2, 0xbfb8aa3b, v152
	v_exp_f32_e32 v2, v2
	s_nop 0
	v_add_f32_e32 v2, 1.0, v2
	v_rcp_f32_e32 v13, v2
	v_mul_f32_e32 v2, 0xbfb8aa3b, v151
	v_exp_f32_e32 v2, v2
	s_nop 0
	v_add_f32_e32 v2, 1.0, v2
	v_rcp_f32_e32 v14, v2
	v_mul_f32_e32 v2, 0xbfb8aa3b, v150
	v_exp_f32_e32 v2, v2
	s_nop 0
	v_add_f32_e32 v2, 1.0, v2
	v_rcp_f32_e32 v15, v2
.LBB0_266:
	v_pk_mul_f32 v[86:87], v[86:87], v[8:9]
	v_pk_mul_f32 v[88:89], v[88:89], v[10:11]
	v_pk_mul_f32 v[82:83], v[82:83], v[12:13]
	s_and_b64 vcc, exec, s[42:43]
	v_pk_mul_f32 v[84:85], v[84:85], v[14:15]
	s_cbranch_vccnz .LBB0_268
	v_cvt_pk_bf16_f32 v2, v86, v87
	v_cvt_pk_bf16_f32 v3, v88, v89
	v_cvt_pk_bf16_f32 v4, v82, v83
	v_cvt_pk_bf16_f32 v5, v84, v85
	global_store_dwordx4 v[0:1], v[2:5], off offset:256 sc1

.LBB0_290:
	v_ashrrev_i32_e32 v227, 31, v226
	v_lshlrev_b64 v[194:195], 11, v[226:227]
	v_pk_mul_f32 v[78:79], v[78:79], v[0:1]
	v_lshl_add_u64 v[0:1], s[96:97], 0, v[194:195]
	v_pk_mul_f32 v[80:81], v[80:81], v[2:3]
	v_pk_mul_f32 v[74:75], v[74:75], v[4:5]
	v_pk_mul_f32 v[76:77], v[76:77], v[6:7]
	s_andn2_b64 vcc, exec, s[14:15]
	v_lshl_add_u64 v[0:1], v[218:219], 1, v[0:1]
	s_cbranch_vccnz .LBB0_292
	v_cvt_pk_bf16_f32 v2, v78, v79
	v_cvt_pk_bf16_f32 v3, v80, v81
	v_cvt_pk_bf16_f32 v4, v74, v75
	v_cvt_pk_bf16_f32 v5, v76, v77
	global_store_dwordx4 v[0:1], v[2:5], off sc1
	s_nop 1
	v_mul_f32_e32 v2, 0xbfb8aa3b, v248
	v_exp_f32_e32 v2, v2
	s_nop 0
	v_add_f32_e32 v2, 1.0, v2
	v_rcp_f32_e32 v8, v2
	v_mul_f32_e32 v2, 0xbfb8aa3b, v247
	v_exp_f32_e32 v2, v2
	s_nop 0
	v_add_f32_e32 v2, 1.0, v2
	v_rcp_f32_e32 v9, v2
	v_mul_f32_e32 v2, 0xbfb8aa3b, v246
	v_exp_f32_e32 v2, v2
	s_nop 0
	v_add_f32_e32 v2, 1.0, v2
	v_rcp_f32_e32 v10, v2
	v_mul_f32_e32 v2, 0xbfb8aa3b, v245
	v_exp_f32_e32 v2, v2
	s_nop 0
	v_add_f32_e32 v2, 1.0, v2
	v_rcp_f32_e32 v11, v2
	v_mul_f32_e32 v2, 0xbfb8aa3b, v244
	v_exp_f32_e32 v2, v2
	s_nop 0
	v_add_f32_e32 v2, 1.0, v2
	v_rcp_f32_e32 v12, v2
	v_mul_f32_e32 v2, 0xbfb8aa3b, v225
	v_exp_f32_e32 v2, v2
	s_nop 0
	v_add_f32_e32 v2, 1.0, v2
	v_rcp_f32_e32 v13, v2
	v_mul_f32_e32 v2, 0xbfb8aa3b, v223
	v_exp_f32_e32 v2, v2
	s_nop 0
	v_add_f32_e32 v2, 1.0, v2
	v_rcp_f32_e32 v14, v2
	v_mul_f32_e32 v2, 0xbfb8aa3b, v221
	v_exp_f32_e32 v2, v2
	s_nop 0
	v_add_f32_e32 v2, 1.0, v2
	v_rcp_f32_e32 v15, v2
.LBB0_292:
	v_pk_mul_f32 v[46:47], v[46:47], v[8:9]
	v_pk_mul_f32 v[48:49], v[48:49], v[10:11]
	v_pk_mul_f32 v[42:43], v[42:43], v[12:13]
	s_and_b64 vcc, exec, s[42:43]
	v_pk_mul_f32 v[44:45], v[44:45], v[14:15]
	s_cbranch_vccnz .LBB0_294
	v_cvt_pk_bf16_f32 v2, v46, v47
	v_cvt_pk_bf16_f32 v3, v48, v49
	v_cvt_pk_bf16_f32 v4, v42, v43
	v_cvt_pk_bf16_f32 v5, v44, v45
	global_store_dwordx4 v[0:1], v[2:5], off offset:256 sc1

.LBB0_300:
	v_ashrrev_i32_e32 v225, 31, v224
	v_lshlrev_b64 v[178:179], 11, v[224:225]
	v_pk_mul_f32 v[70:71], v[70:71], v[0:1]
	v_lshl_add_u64 v[0:1], s[96:97], 0, v[178:179]
	v_pk_mul_f32 v[72:73], v[72:73], v[2:3]
	v_pk_mul_f32 v[66:67], v[66:67], v[4:5]
	v_pk_mul_f32 v[68:69], v[68:69], v[6:7]
	s_andn2_b64 vcc, exec, s[14:15]
	v_lshl_add_u64 v[0:1], v[218:219], 1, v[0:1]
	s_cbranch_vccnz .LBB0_302
	v_cvt_pk_bf16_f32 v2, v70, v71
	v_cvt_pk_bf16_f32 v3, v72, v73
	v_cvt_pk_bf16_f32 v4, v66, v67
	v_cvt_pk_bf16_f32 v5, v68, v69
	global_store_dwordx4 v[0:1], v[2:5], off sc1
	s_nop 1
	v_mul_f32_e32 v2, 0xbfb8aa3b, v190
	v_exp_f32_e32 v2, v2
	s_nop 0
	v_add_f32_e32 v2, 1.0, v2
	v_rcp_f32_e32 v8, v2
	v_mul_f32_e32 v2, 0xbfb8aa3b, v189
	v_exp_f32_e32 v2, v2
	s_nop 0
	v_add_f32_e32 v2, 1.0, v2
	v_rcp_f32_e32 v9, v2
	v_mul_f32_e32 v2, 0xbfb8aa3b, v188
	v_exp_f32_e32 v2, v2
	s_nop 0
	v_add_f32_e32 v2, 1.0, v2
	v_rcp_f32_e32 v10, v2
	v_mul_f32_e32 v2, 0xbfb8aa3b, v187
	v_exp_f32_e32 v2, v2
	s_nop 0
	v_add_f32_e32 v2, 1.0, v2
	v_rcp_f32_e32 v11, v2
	v_mul_f32_e32 v2, 0xbfb8aa3b, v186
	v_exp_f32_e32 v2, v2
	s_nop 0
	v_add_f32_e32 v2, 1.0, v2
	v_rcp_f32_e32 v12, v2
	v_mul_f32_e32 v2, 0xbfb8aa3b, v184
	v_exp_f32_e32 v2, v2
	s_nop 0
	v_add_f32_e32 v2, 1.0, v2
	v_rcp_f32_e32 v13, v2
	v_mul_f32_e32 v2, 0xbfb8aa3b, v183
	v_exp_f32_e32 v2, v2
	s_nop 0
	v_add_f32_e32 v2, 1.0, v2
	v_rcp_f32_e32 v14, v2
	v_mul_f32_e32 v2, 0xbfb8aa3b, v182
	v_exp_f32_e32 v2, v2
	s_nop 0
	v_add_f32_e32 v2, 1.0, v2
	v_rcp_f32_e32 v15, v2
.LBB0_302:
	v_pk_mul_f32 v[38:39], v[38:39], v[8:9]
	v_pk_mul_f32 v[40:41], v[40:41], v[10:11]
	v_pk_mul_f32 v[34:35], v[34:35], v[12:13]
	s_and_b64 vcc, exec, s[42:43]
	v_pk_mul_f32 v[36:37], v[36:37], v[14:15]
	s_cbranch_vccnz .LBB0_304
	v_cvt_pk_bf16_f32 v2, v38, v39
	v_cvt_pk_bf16_f32 v3, v40, v41
	v_cvt_pk_bf16_f32 v4, v34, v35
	v_cvt_pk_bf16_f32 v5, v36, v37
	global_store_dwordx4 v[0:1], v[2:5], off offset:256 sc1

.LBB0_310:
	v_ashrrev_i32_e32 v223, 31, v222
	v_lshlrev_b64 v[162:163], 11, v[222:223]
	v_pk_mul_f32 v[62:63], v[62:63], v[0:1]
	v_lshl_add_u64 v[0:1], s[96:97], 0, v[162:163]
	v_pk_mul_f32 v[64:65], v[64:65], v[2:3]
	v_pk_mul_f32 v[58:59], v[58:59], v[4:5]
	v_pk_mul_f32 v[60:61], v[60:61], v[6:7]
	s_andn2_b64 vcc, exec, s[14:15]
	v_lshl_add_u64 v[0:1], v[218:219], 1, v[0:1]
	s_cbranch_vccnz .LBB0_312
	v_cvt_pk_bf16_f32 v2, v62, v63
	v_cvt_pk_bf16_f32 v3, v64, v65
	v_cvt_pk_bf16_f32 v4, v58, v59
	v_cvt_pk_bf16_f32 v5, v60, v61
	global_store_dwordx4 v[0:1], v[2:5], off sc1
	s_nop 1
	v_mul_f32_e32 v2, 0xbfb8aa3b, v174
	v_exp_f32_e32 v2, v2
	s_nop 0
	v_add_f32_e32 v2, 1.0, v2
	v_rcp_f32_e32 v8, v2
	v_mul_f32_e32 v2, 0xbfb8aa3b, v173
	v_exp_f32_e32 v2, v2
	s_nop 0
	v_add_f32_e32 v2, 1.0, v2
	v_rcp_f32_e32 v9, v2
	v_mul_f32_e32 v2, 0xbfb8aa3b, v172
	v_exp_f32_e32 v2, v2
	s_nop 0
	v_add_f32_e32 v2, 1.0, v2
	v_rcp_f32_e32 v10, v2
	v_mul_f32_e32 v2, 0xbfb8aa3b, v171
	v_exp_f32_e32 v2, v2
	s_nop 0
	v_add_f32_e32 v2, 1.0, v2
	v_rcp_f32_e32 v11, v2
	v_mul_f32_e32 v2, 0xbfb8aa3b, v170
	v_exp_f32_e32 v2, v2
	s_nop 0
	v_add_f32_e32 v2, 1.0, v2
	v_rcp_f32_e32 v12, v2
	v_mul_f32_e32 v2, 0xbfb8aa3b, v168
	v_exp_f32_e32 v2, v2
	s_nop 0
	v_add_f32_e32 v2, 1.0, v2
	v_rcp_f32_e32 v13, v2
	v_mul_f32_e32 v2, 0xbfb8aa3b, v167
	v_exp_f32_e32 v2, v2
	s_nop 0
	v_add_f32_e32 v2, 1.0, v2
	v_rcp_f32_e32 v14, v2
	v_mul_f32_e32 v2, 0xbfb8aa3b, v166
	v_exp_f32_e32 v2, v2
	s_nop 0
	v_add_f32_e32 v2, 1.0, v2
	v_rcp_f32_e32 v15, v2
.LBB0_312:
	v_pk_mul_f32 v[30:31], v[30:31], v[8:9]
	v_pk_mul_f32 v[32:33], v[32:33], v[10:11]
	v_pk_mul_f32 v[26:27], v[26:27], v[12:13]
	s_and_b64 vcc, exec, s[42:43]
	v_pk_mul_f32 v[28:29], v[28:29], v[14:15]
	s_cbranch_vccnz .LBB0_314
	v_cvt_pk_bf16_f32 v2, v30, v31
	v_cvt_pk_bf16_f32 v3, v32, v33
	v_cvt_pk_bf16_f32 v4, v26, v27
	v_cvt_pk_bf16_f32 v5, v28, v29
	global_store_dwordx4 v[0:1], v[2:5], off offset:256 sc1

.LBB0_320:
	v_ashrrev_i32_e32 v221, 31, v220
	s_waitcnt vmcnt(0) lgkmcnt(0)
	v_lshlrev_b64 v[146:147], 11, v[220:221]
	v_pk_mul_f32 v[54:55], v[54:55], v[0:1]
	v_lshl_add_u64 v[0:1], s[96:97], 0, v[146:147]
	v_pk_mul_f32 v[56:57], v[56:57], v[2:3]
	v_pk_mul_f32 v[50:51], v[50:51], v[4:5]
	v_pk_mul_f32 v[52:53], v[52:53], v[6:7]
	s_andn2_b64 vcc, exec, s[14:15]
	v_lshl_add_u64 v[0:1], v[218:219], 1, v[0:1]
	s_cbranch_vccnz .LBB0_322
	v_cvt_pk_bf16_f32 v2, v54, v55
	v_cvt_pk_bf16_f32 v3, v56, v57
	v_cvt_pk_bf16_f32 v4, v50, v51
	v_cvt_pk_bf16_f32 v5, v52, v53
	global_store_dwordx4 v[0:1], v[2:5], off sc1
	s_nop 1
	v_mul_f32_e32 v2, 0xbfb8aa3b, v158
	v_exp_f32_e32 v2, v2
	s_nop 0
	v_add_f32_e32 v2, 1.0, v2
	v_rcp_f32_e32 v8, v2
	v_mul_f32_e32 v2, 0xbfb8aa3b, v157
	v_exp_f32_e32 v2, v2
	s_nop 0
	v_add_f32_e32 v2, 1.0, v2
	v_rcp_f32_e32 v9, v2
	v_mul_f32_e32 v2, 0xbfb8aa3b, v156
	v_exp_f32_e32 v2, v2
	s_nop 0
	v_add_f32_e32 v2, 1.0, v2
	v_rcp_f32_e32 v10, v2
	v_mul_f32_e32 v2, 0xbfb8aa3b, v155
	v_exp_f32_e32 v2, v2
	s_nop 0
	v_add_f32_e32 v2, 1.0, v2
	v_rcp_f32_e32 v11, v2
	v_mul_f32_e32 v2, 0xbfb8aa3b, v154
	v_exp_f32_e32 v2, v2
	s_nop 0
	v_add_f32_e32 v2, 1.0, v2
	v_rcp_f32_e32 v12, v2
	v_mul_f32_e32 v2, 0xbfb8aa3b, v152
	v_exp_f32_e32 v2, v2
	s_nop 0
	v_add_f32_e32 v2, 1.0, v2
	v_rcp_f32_e32 v13, v2
	v_mul_f32_e32 v2, 0xbfb8aa3b, v151
	v_exp_f32_e32 v2, v2
	s_nop 0
	v_add_f32_e32 v2, 1.0, v2
	v_rcp_f32_e32 v14, v2
	v_mul_f32_e32 v2, 0xbfb8aa3b, v150
	v_exp_f32_e32 v2, v2
	s_nop 0
	v_add_f32_e32 v2, 1.0, v2
	v_rcp_f32_e32 v15, v2
.LBB0_322:
	v_pk_mul_f32 v[22:23], v[22:23], v[8:9]
	v_pk_mul_f32 v[24:25], v[24:25], v[10:11]
	v_pk_mul_f32 v[18:19], v[18:19], v[12:13]
	s_and_b64 vcc, exec, s[42:43]
	v_pk_mul_f32 v[20:21], v[20:21], v[14:15]
	s_cbranch_vccnz .LBB0_324
	v_cvt_pk_bf16_f32 v2, v22, v23
	v_cvt_pk_bf16_f32 v3, v24, v25
	v_cvt_pk_bf16_f32 v4, v18, v19
	v_cvt_pk_bf16_f32 v5, v20, v21
	global_store_dwordx4 v[0:1], v[2:5], off offset:256 sc1
